# PD1: GEMM phase prologue issues K-tile-1 LDS-DMA loads together with K-tile-0 (one counted wait), on top of v052
# speedup vs baseline: 1.0053x; 1.0053x over previous
.LBB0_156:
	s_andn2_b64 vcc, exec, s[22:23]
	s_cbranch_vccnz .LBB0_228
	s_waitcnt lgkmcnt(0)
	v_bfe_i32 v3, v14, 27, 1
	v_lshlrev_b32_e32 v1, 4, v14
	v_lshrrev_b32_e32 v3, 22, v3
	v_add_u32_e32 v3, v1, v3
	v_and_b32_e32 v3, 0xfffffc00, v3
	v_ashrrev_i32_e32 v2, 31, v14
	v_sub_u32_e32 v3, v1, v3
	v_lshrrev_b32_e32 v2, 26, v2
	v_lshrrev_b32_e32 v4, 4, v3
	v_add_u32_e32 v2, v14, v2
	v_bitop3_b32 v4, v4, v3, 32 bitop3:0x6c
	v_ashrrev_i32_e32 v3, 31, v3
	v_ashrrev_i32_e32 v2, 6, v2
	v_lshrrev_b32_e32 v3, 26, v3
	v_lshlrev_b32_e32 v5, 3, v2
	v_add_u32_e32 v3, v4, v3
	v_and_b32_e32 v5, -16, v5
	v_ashrrev_i32_e32 v3, 6, v3
	v_lshlrev_b32_e32 v2, 5, v2
	v_add_u32_e32 v5, v3, v5
	v_and_b32_e32 v15, 32, v2
	v_mul_i32_i24_e32 v2, 64, v3
	v_sub_u32_e32 v2, v4, v2
	v_lshlrev_b32_e32 v4, 1, v5
	v_lshrrev_b32_e32 v6, 2, v5
	v_and_b32_e32 v3, 3, v3
	s_mov_b32 s2, 0x7fffffe0
	v_ashrrev_i16_sdwa v2, v222, sext(v2) dst_sel:DWORD dst_unused:UNUSED_PAD src0_sel:DWORD src1_sel:BYTE_0
	v_and_b32_e32 v4, 24, v4
	v_and_b32_e32 v6, 4, v6
	v_and_or_b32 v3, v5, s2, v3
	v_bfe_i32 v16, v2, 0, 16
	v_or3_b32 v3, v3, v6, v4
	v_add_u32_e32 v2, v15, v16
	v_mul_lo_u32 v17, v5, s39
	v_mul_lo_u32 v3, v3, s38
	v_add_u32_e32 v1, 0x2000, v1
	v_add_lshl_u32 v186, v2, v17, 1
	v_add_lshl_u32 v188, v3, v2, 1
	v_ashrrev_i32_e32 v2, 31, v1
	v_lshrrev_b32_e32 v2, 22, v2
	v_add_u32_e32 v2, v1, v2
	v_ashrrev_i32_e32 v2, 10, v2
	v_mul_i32_i24_e32 v3, 0x400, v2
	v_sub_u32_e32 v1, v1, v3
	v_lshrrev_b32_e32 v3, 4, v1
	v_bitop3_b32 v1, v3, v1, 32 bitop3:0x6c
	v_ashrrev_i32_e32 v4, 31, v1
	s_lshl_b32 s16, s39, 8
	v_lshrrev_b32_e32 v4, 26, v4
	s_lshl_b64 s[62:63], s[16:17], 1
	s_ashr_i32 s21, s99, 31
	v_writelane_b32 v243, s59, 32
	v_lshlrev_b32_e32 v3, 3, v2
	v_add_u32_e32 v4, v1, v4
	s_mul_i32 s21, s62, s21
	s_mul_hi_u32 s22, s62, s99
	v_writelane_b32 v243, s56, 42
	v_and_b32_e32 v3, -16, v3
	v_ashrrev_i32_e32 v5, 6, v4
	s_add_i32 s21, s22, s21
	s_bfe_u32 s22, s39, 0x10017
	v_writelane_b32 v243, s57, 43
	s_ashr_i32 s1, s0, 6
	v_add_u32_e32 v3, v5, v3
	v_lshlrev_b32_e32 v2, 5, v2
	v_and_b32_e32 v5, 3, v5
	s_lshl_b32 s56, s38, 9
	s_mul_i32 s22, s22, s99
	v_and_b32_e32 v18, 32, v2
	v_and_b32_e32 v2, 0xc0, v4
	v_and_or_b32 v5, v3, s2, v5
	s_ashr_i32 s2, s0, 8
	s_lshl_b32 s69, s38, 8
	s_lshl_b32 s57, s1, 10
	s_add_i32 s21, s21, s22
	s_mul_i32 s23, s56, s88
	v_sub_u32_e32 v1, v1, v2
	v_lshlrev_b32_e32 v2, 1, v3
	v_lshrrev_b32_e32 v4, 2, v3
	s_mul_hi_i32 s22, s56, s88
	s_add_u32 s34, s48, s23
	v_ashrrev_i16_sdwa v1, v222, sext(v1) dst_sel:DWORD dst_unused:UNUSED_PAD src0_sel:DWORD src1_sel:BYTE_0
	v_and_b32_e32 v2, 24, v2
	v_and_b32_e32 v4, 4, v4
	s_addc_u32 s35, s49, s22
	s_add_i32 s90, s57, 0
	v_bfe_i32 v19, v1, 0, 16
	v_or3_b32 v2, v5, v4, v2
	s_add_i32 m0, s90, 0x10000
	v_add_u32_e32 v1, v18, v19
	v_mul_lo_u32 v2, v2, s38
	global_load_lds_dwordx4 v188, s[34:35]
	s_add_i32 m0, s90, 0x12000
	v_add_lshl_u32 v192, v2, v1, 1
	s_add_u32 s22, s34, s69
	global_load_lds_dwordx4 v192, s[34:35]
	s_addc_u32 s23, s35, 0
	s_add_i32 m0, s90, 0x14000
	v_mul_lo_u32 v20, v3, s39
	s_mul_i32 s39, s62, s99
	global_load_lds_dwordx4 v188, s[22:23]
	s_add_i32 m0, s90, 0x16000
	s_add_u32 s80, s54, s39
	v_mov_b32_e32 v189, v0
	v_mov_b32_e32 v193, v0
	s_addc_u32 s81, s55, s21
	s_add_i32 s60, s90, 0x2000
	global_load_lds_dwordx4 v192, s[22:23]
	s_mov_b32 m0, s90
	s_add_u32 s22, s80, s16
	v_add_lshl_u32 v190, v1, v20, 1
	global_load_lds_dwordx4 v186, s[80:81]
	s_mov_b32 m0, s60
	s_addc_u32 s23, s81, 0
	s_add_i32 s61, s90, 0x4000
	global_load_lds_dwordx4 v190, s[80:81]
	s_mov_b32 m0, s61
	s_add_i32 s71, s90, 0x6000
	global_load_lds_dwordx4 v186, s[22:23]
	s_mov_b32 m0, s71
	v_writelane_b32 v243, s47, 40
	global_load_lds_dwordx4 v190, s[22:23]
	s_add_u32 s100, s34, s69
	s_addc_u32 s101, s35, 0
	s_add_i32 s64, s90, 0x8000
	s_add_i32 s65, s90, 0xa000
	s_add_i32 m0, s90, 0x17f80
	s_nop 0
	global_load_lds_dwordx4 v188, s[34:35] offset:128
	s_add_i32 m0, s90, 0x19f80
	s_nop 0
	global_load_lds_dwordx4 v192, s[34:35] offset:128
	s_add_i32 m0, s90, 0x7f80
	s_nop 0
	global_load_lds_dwordx4 v186, s[80:81] offset:128
	s_add_i32 m0, s90, 0x9f80
	s_nop 0
	global_load_lds_dwordx4 v190, s[80:81] offset:128
	s_add_i32 m0, s90, 0x1bf80
	s_nop 0
	global_load_lds_dwordx4 v188, s[100:101] offset:128
	s_add_i32 m0, s90, 0x1df80
	s_nop 0
	global_load_lds_dwordx4 v192, s[100:101] offset:128
	s_add_i32 m0, s90, 0x1e000
	v_writelane_b32 v243, s52, 44
	s_cmp_eq_u32 s2, 1
	v_mov_b32_e32 v187, v0
	v_writelane_b32 v243, s53, 45
	v_mov_b32_e32 v191, v0
	s_cselect_b64 s[22:23], -1, 0
	v_writelane_b32 v243, s22, 30
	s_cmp_lg_u32 s2, 1
	s_nop 0
	v_writelane_b32 v243, s23, 31
	s_cbranch_scc1 .LBB0_159
	s_barrier
.LBB0_159:
	s_waitcnt vmcnt(8)
	s_barrier
	v_and_b32_e32 v4, 15, v14
	v_lshlrev_b32_e32 v5, 2, v14
	v_bfe_u32 v3, v14, 4, 2
	v_lshlrev_b32_e32 v233, 4, v3
	s_and_b32 s1, s1, 3
	s_lshr_b32 s91, s38, 6
	v_lshl_or_b32 v1, s2, 6, v4
	v_lshl_or_b32 v4, v4, 6, v233
	s_lshl_b32 s2, s2, 13
	v_and_b32_e32 v5, 32, v5
	v_bitop3_b32 v6, v4, s2, v5 bitop3:0xde
	s_lshl_b32 s2, s1, 12
	s_add_i32 s68, s91, -2
	s_cmpk_lt_u32 s0, 0x100
	s_cselect_b64 s[22:23], -1, 0
	v_writelane_b32 v243, s22, 28
	v_bitop3_b32 v234, v4, s2, v5 bitop3:0xde
	s_lshl_b32 s0, s1, 6
	v_writelane_b32 v243, s23, 29
	s_lshl_b32 s2, s74, 3
	v_writelane_b32 v243, s42, 46
	s_cmp_lg_u64 s[42:43], 0
	s_cselect_b64 s[22:23], -1, 0
	v_writelane_b32 v243, s43, 47
	v_readlane_b32 s40, v248, 54
	v_readlane_b32 s41, v248, 55
	v_writelane_b32 v243, s22, 48
	s_cmp_lg_u64 s[40:41], 0
	v_lshlrev_b32_e32 v2, 3, v3
	v_writelane_b32 v243, s23, 49
	s_cselect_b64 s[22:23], -1, 0
	s_abs_i32 s52, s2
	v_cmp_eq_u32_e64 s[38:39], 0, v3
	v_cvt_f32_u32_e32 v3, s52
	v_readlane_b32 s42, v248, 56
	v_readlane_b32 s43, v248, 57
	s_and_b32 s41, s41, 0xffff
	v_rcp_iflag_f32_e32 v3, v3
	v_writelane_b32 v248, s40, 54
	v_writelane_b32 v243, s22, 50
	v_or_b32_e32 v236, s0, v2
	v_writelane_b32 v248, s41, 55
	v_mul_f32_e32 v3, 0x4f7ffffe, v3
	v_writelane_b32 v243, s23, 51
	v_writelane_b32 v248, s42, 56
	v_cvt_u32_f32_e32 v3, v3
	v_writelane_b32 v248, s43, 57
	v_readlane_b32 s40, v243, 5
	v_readlane_b32 s41, v243, 6
	v_writelane_b32 v243, s0, 52
	s_mov_b32 s0, s74
	v_writelane_b32 v243, s0, 53
	s_bfe_i32 s0, s0, 0x1001c
	v_lshl_or_b32 v237, s1, 5, v2
	v_writelane_b32 v243, s0, 38
	s_sub_i32 s0, 0, s52
	v_readfirstlane_b32 s1, v3
	v_add_u32_e32 v3, v17, v15
	s_waitcnt vmcnt(6)
	s_mul_i32 s0, s0, s1
	v_add_lshl_u32 v4, v3, v16, 1
	v_mov_b32_e32 v5, v0
	v_add_u32_e32 v3, v20, v18
	s_mul_hi_u32 s0, s1, s0
	v_lshl_add_u64 v[194:195], s[16:17], 0, v[4:5]
	v_add_lshl_u32 v4, v3, v19, 1
	s_mov_b32 s46, 0
	v_or_b32_e32 v235, 64, v233
	s_mov_b32 s45, s17
	s_lshl_b32 s22, s29, 15
	s_mov_b32 s23, s43
	s_and_b32 s21, s41, 0xffff
	s_mov_b32 s28, s2
	s_mov_b32 s59, s58
	s_mov_b32 s74, s58
	s_mov_b32 s75, s58
	s_mov_b32 s84, s58
	s_mov_b32 s85, s58
	s_add_i32 s0, s1, s0
	s_lshl_b32 s53, s29, 4
	v_lshl_add_u64 v[196:197], s[16:17], 0, v[4:5]
	v_add_u32_e32 v238, 0, v6
	v_lshlrev_b32_e32 v239, 2, v2
	s_barrier
	v_writelane_b32 v243, s0, 34
	s_branch .LBB0_162
